# GEMM K-loop heads aligned to 256 bytes (code placement)
# speedup vs baseline: 1.0014x; 1.0012x over previous
.LBB0_244:
	s_ashr_i32 s53, s52, 31
	s_lshl_b64 s[12:13], s[52:53], 20
	v_readlane_b32 s11, v243, 37
	s_add_u32 s54, s11, s12
	v_readlane_b32 s11, v243, 38
	s_addc_u32 s55, s11, s13
	s_and_b64 s[12:13], s[40:41], exec
	s_cselect_b32 s11, s55, s43
	s_cselect_b32 s53, s54, s42
	s_ashr_i32 s51, s50, 31
	s_lshl_b64 s[12:13], s[50:51], 20
	s_add_u32 s58, s91, s12
	s_addc_u32 s59, s97, s13
	s_and_b64 s[12:13], s[40:41], exec
	s_cselect_b32 s51, s59, s73
	s_cselect_b32 vcc_lo, s58, s72
	s_add_u32 s42, s42, 0x80080
	s_addc_u32 s43, s43, 0
	s_add_u32 vcc_hi, s72, 0x100
	v_mov_b32_e32 v0, 0
	s_addc_u32 s12, s73, 0
	s_mov_b32 s13, -2
	v_mov_b32_e32 v1, v0
	v_mov_b32_e32 v2, v0
	v_mov_b32_e32 v3, v0
	v_mov_b32_e32 v4, v0
	v_mov_b32_e32 v5, v0
	v_mov_b32_e32 v6, v0
	v_mov_b32_e32 v7, v0
	v_mov_b32_e32 v16, v0
	v_mov_b32_e32 v17, v0
	v_mov_b32_e32 v18, v0
	v_mov_b32_e32 v19, v0
	v_mov_b32_e32 v20, v0
	v_mov_b32_e32 v21, v0
	v_mov_b32_e32 v22, v0
	v_mov_b32_e32 v23, v0
	s_waitcnt vmcnt(0)
	v_mov_b32_e32 v32, v0
	v_mov_b32_e32 v33, v0
	v_mov_b32_e32 v34, v0
	v_mov_b32_e32 v35, v0
	v_mov_b32_e32 v36, v0
	v_mov_b32_e32 v37, v0
	v_mov_b32_e32 v38, v0
	v_mov_b32_e32 v39, v0
	v_mov_b32_e32 v48, v0
	v_mov_b32_e32 v49, v0
	v_mov_b32_e32 v50, v0
	v_mov_b32_e32 v51, v0
	v_mov_b32_e32 v52, v0
	v_mov_b32_e32 v53, v0
	v_mov_b32_e32 v54, v0
	v_mov_b32_e32 v55, v0
	v_mov_b32_e32 v8, v0
	v_mov_b32_e32 v9, v0
	v_mov_b32_e32 v10, v0
	v_mov_b32_e32 v11, v0
	v_mov_b32_e32 v12, v0
	v_mov_b32_e32 v13, v0
	v_mov_b32_e32 v14, v0
	v_mov_b32_e32 v15, v0
	v_mov_b32_e32 v24, v0
	v_mov_b32_e32 v25, v0
	v_mov_b32_e32 v26, v0
	v_mov_b32_e32 v27, v0
	v_mov_b32_e32 v28, v0
	v_mov_b32_e32 v29, v0
	v_mov_b32_e32 v30, v0
	v_mov_b32_e32 v31, v0
	v_mov_b32_e32 v40, v0
	v_mov_b32_e32 v41, v0
	v_mov_b32_e32 v42, v0
	v_mov_b32_e32 v43, v0
	v_mov_b32_e32 v44, v0
	v_mov_b32_e32 v45, v0
	v_mov_b32_e32 v46, v0
	v_mov_b32_e32 v47, v0
	v_mov_b32_e32 v72, v0
	v_mov_b32_e32 v73, v0
	v_mov_b32_e32 v74, v0
	v_mov_b32_e32 v75, v0
	v_mov_b32_e32 v76, v0
	v_mov_b32_e32 v77, v0
	v_mov_b32_e32 v78, v0
	v_mov_b32_e32 v79, v0
	v_mov_b32_e32 v80, v0
	v_mov_b32_e32 v81, v0
	v_mov_b32_e32 v82, v0
	v_mov_b32_e32 v83, v0
	v_mov_b32_e32 v84, v0
	v_mov_b32_e32 v85, v0
	v_mov_b32_e32 v86, v0
	v_mov_b32_e32 v87, v0
	v_mov_b32_e32 v96, v0
	v_mov_b32_e32 v97, v0
	v_mov_b32_e32 v98, v0
	v_mov_b32_e32 v99, v0
	v_mov_b32_e32 v100, v0
	v_mov_b32_e32 v101, v0
	v_mov_b32_e32 v102, v0
	v_mov_b32_e32 v103, v0
	v_mov_b32_e32 v112, v0
	v_mov_b32_e32 v113, v0
	v_mov_b32_e32 v114, v0
	v_mov_b32_e32 v115, v0
	v_mov_b32_e32 v116, v0
	v_mov_b32_e32 v117, v0
	v_mov_b32_e32 v118, v0
	v_mov_b32_e32 v119, v0
	v_mov_b32_e32 v128, v0
	v_mov_b32_e32 v129, v0
	v_mov_b32_e32 v130, v0
	v_mov_b32_e32 v131, v0
	v_mov_b32_e32 v132, v0
	v_mov_b32_e32 v133, v0
	v_mov_b32_e32 v134, v0
	v_mov_b32_e32 v135, v0
	v_mov_b32_e32 v88, v0
	v_mov_b32_e32 v89, v0
	v_mov_b32_e32 v90, v0
	v_mov_b32_e32 v91, v0
	v_mov_b32_e32 v92, v0
	v_mov_b32_e32 v93, v0
	v_mov_b32_e32 v94, v0
	v_mov_b32_e32 v95, v0
	v_mov_b32_e32 v104, v0
	v_mov_b32_e32 v105, v0
	v_mov_b32_e32 v106, v0
	v_mov_b32_e32 v107, v0
	v_mov_b32_e32 v108, v0
	v_mov_b32_e32 v109, v0
	v_mov_b32_e32 v110, v0
	v_mov_b32_e32 v111, v0
	v_mov_b32_e32 v120, v0
	v_mov_b32_e32 v121, v0
	v_mov_b32_e32 v122, v0
	v_mov_b32_e32 v123, v0
	v_mov_b32_e32 v124, v0
	v_mov_b32_e32 v125, v0
	v_mov_b32_e32 v126, v0
	v_mov_b32_e32 v127, v0
	v_mov_b32_e32 v136, v0
	v_mov_b32_e32 v137, v0
	v_mov_b32_e32 v138, v0
	v_mov_b32_e32 v139, v0
	v_mov_b32_e32 v140, v0
	v_mov_b32_e32 v141, v0
	v_mov_b32_e32 v142, v0
	v_mov_b32_e32 v143, v0
	.p2alignl 8, 3212836864

.LBB0_712:
	s_ashr_i32 s51, s50, 31
	s_lshl_b64 s[10:11], s[50:51], 20
	v_readlane_b32 s12, v243, 48
	s_add_u32 s52, s12, s10
	v_readlane_b32 s10, v243, 49
	s_addc_u32 s53, s10, s11
	s_and_b64 s[10:11], s[40:41], exec
	s_cselect_b32 s10, s53, s59
	s_cselect_b32 s11, s52, s58
	s_ashr_i32 s49, s48, 31
	s_lshl_b64 s[12:13], s[48:49], 20
	s_add_u32 s54, s5, s12
	s_addc_u32 s55, s6, s13
	s_and_b64 s[12:13], s[40:41], exec
	s_cselect_b32 s49, s55, s73
	s_cselect_b32 s51, s54, s72
	s_add_u32 s58, s58, 0x80080
	s_addc_u32 s59, s59, 0
	s_add_u32 s97, s72, 0x100
	v_mov_b32_e32 v0, 0
	s_addc_u32 s12, s73, 0
	s_mov_b32 s13, -2
	v_mov_b32_e32 v1, v0
	v_mov_b32_e32 v2, v0
	v_mov_b32_e32 v3, v0
	v_mov_b32_e32 v4, v0
	v_mov_b32_e32 v5, v0
	v_mov_b32_e32 v6, v0
	v_mov_b32_e32 v7, v0
	v_mov_b32_e32 v12, v0
	v_mov_b32_e32 v13, v0
	v_mov_b32_e32 v14, v0
	v_mov_b32_e32 v15, v0
	v_mov_b32_e32 v20, v0
	v_mov_b32_e32 v21, v0
	v_mov_b32_e32 v22, v0
	v_mov_b32_e32 v23, v0
	v_mov_b32_e32 v28, v0
	v_mov_b32_e32 v29, v0
	v_mov_b32_e32 v30, v0
	v_mov_b32_e32 v31, v0
	s_waitcnt vmcnt(0)
	v_mov_b32_e32 v36, v0
	v_mov_b32_e32 v37, v0
	v_mov_b32_e32 v38, v0
	v_mov_b32_e32 v39, v0
	v_mov_b32_e32 v44, v0
	v_mov_b32_e32 v45, v0
	v_mov_b32_e32 v46, v0
	v_mov_b32_e32 v47, v0
	v_mov_b32_e32 v52, v0
	v_mov_b32_e32 v53, v0
	v_mov_b32_e32 v54, v0
	v_mov_b32_e32 v55, v0
	v_mov_b32_e32 v8, v0
	v_mov_b32_e32 v9, v0
	v_mov_b32_e32 v10, v0
	v_mov_b32_e32 v11, v0
	v_mov_b32_e32 v16, v0
	v_mov_b32_e32 v17, v0
	v_mov_b32_e32 v18, v0
	v_mov_b32_e32 v19, v0
	v_mov_b32_e32 v24, v0
	v_mov_b32_e32 v25, v0
	v_mov_b32_e32 v26, v0
	v_mov_b32_e32 v27, v0
	v_mov_b32_e32 v32, v0
	v_mov_b32_e32 v33, v0
	v_mov_b32_e32 v34, v0
	v_mov_b32_e32 v35, v0
	v_mov_b32_e32 v40, v0
	v_mov_b32_e32 v41, v0
	v_mov_b32_e32 v42, v0
	v_mov_b32_e32 v43, v0
	v_mov_b32_e32 v48, v0
	v_mov_b32_e32 v49, v0
	v_mov_b32_e32 v50, v0
	v_mov_b32_e32 v51, v0
	v_mov_b32_e32 v56, v0
	v_mov_b32_e32 v57, v0
	v_mov_b32_e32 v58, v0
	v_mov_b32_e32 v59, v0
	v_mov_b32_e32 v60, v0
	v_mov_b32_e32 v61, v0
	v_mov_b32_e32 v62, v0
	v_mov_b32_e32 v63, v0
	v_mov_b32_e32 v64, v0
	v_mov_b32_e32 v65, v0
	v_mov_b32_e32 v66, v0
	v_mov_b32_e32 v67, v0
	v_mov_b32_e32 v68, v0
	v_mov_b32_e32 v69, v0
	v_mov_b32_e32 v70, v0
	v_mov_b32_e32 v71, v0
	v_mov_b32_e32 v80, v0
	v_mov_b32_e32 v81, v0
	v_mov_b32_e32 v82, v0
	v_mov_b32_e32 v83, v0
	v_mov_b32_e32 v84, v0
	v_mov_b32_e32 v85, v0
	v_mov_b32_e32 v86, v0
	v_mov_b32_e32 v87, v0
	v_mov_b32_e32 v112, v0
	v_mov_b32_e32 v113, v0
	v_mov_b32_e32 v114, v0
	v_mov_b32_e32 v115, v0
	v_mov_b32_e32 v116, v0
	v_mov_b32_e32 v117, v0
	v_mov_b32_e32 v118, v0
	v_mov_b32_e32 v119, v0
	v_mov_b32_e32 v128, v0
	v_mov_b32_e32 v129, v0
	v_mov_b32_e32 v130, v0
	v_mov_b32_e32 v131, v0
	v_mov_b32_e32 v132, v0
	v_mov_b32_e32 v133, v0
	v_mov_b32_e32 v134, v0
	v_mov_b32_e32 v135, v0
	v_mov_b32_e32 v72, v0
	v_mov_b32_e32 v73, v0
	v_mov_b32_e32 v74, v0
	v_mov_b32_e32 v75, v0
	v_mov_b32_e32 v76, v0
	v_mov_b32_e32 v77, v0
	v_mov_b32_e32 v78, v0
	v_mov_b32_e32 v79, v0
	v_mov_b32_e32 v88, v0
	v_mov_b32_e32 v89, v0
	v_mov_b32_e32 v90, v0
	v_mov_b32_e32 v91, v0
	v_mov_b32_e32 v92, v0
	v_mov_b32_e32 v93, v0
	v_mov_b32_e32 v94, v0
	v_mov_b32_e32 v95, v0
	v_mov_b32_e32 v120, v0
	v_mov_b32_e32 v121, v0
	v_mov_b32_e32 v122, v0
	v_mov_b32_e32 v123, v0
	v_mov_b32_e32 v124, v0
	v_mov_b32_e32 v125, v0
	v_mov_b32_e32 v126, v0
	v_mov_b32_e32 v127, v0
	v_mov_b32_e32 v136, v0
	v_mov_b32_e32 v137, v0
	v_mov_b32_e32 v138, v0
	v_mov_b32_e32 v139, v0
	v_mov_b32_e32 v140, v0
	v_mov_b32_e32 v141, v0
	v_mov_b32_e32 v142, v0
	v_mov_b32_e32 v143, v0
	.p2alignl 8, 3212836864
